# c11 + in-projection GEMM: the 4 transposed 'av' column tiles are computed with the operand panels exchanged (A=weights, B=tokens) so the plain store path writes [d][token] directly: no LDS transposes,
# speedup vs baseline: 1.0065x; 1.0065x over previous
; #define PG8_STAGE(bufoff, gbase, voff) do { _Pragma("unroll") for (int _i = 0; _i < 2; ++_i) \
;         __builtin_amdgcn_global_load_lds((const unsigned*)((const char*)(gbase) + (voff)[_i]), (PG8_LAS unsigned*)(lds + (bufoff) + ldsw + _i * 8192), 16, 0, 0); } while (0)
; #define PG8_WAIT_V(n) asm volatile("s_waitcnt vmcnt(" #n ")" ::: "memory")
; #define PG8_BAR __builtin_amdgcn_s_barrier()
; template <class Epi, class Sched, bool ALIGN_EPI = false, bool SP2 = false>
; __device__ __forceinline__ void gemm_phase(PG8_LAS unsigned char* lds, const Gemm g, const Sched& S, const Epi& E) {
;     ...
;     const char* cA = (const char*)g.A + (size_t)cur.pm * tstep; const char* cB = (const char*)g.Bt + (size_t)cur.pn * tstep;
;     S.a_ready(cur);
;     if constexpr (SP2) {
;         PG8_STAGE(PG8_SB(0, 0), cB, voffB); PG8_STAGE(PG8_SB(0, 1), cB + hstep, voffB); PG8_STAGE(PG8_SA(0, 0), cA, voffA); PG8_STAGE(PG8_SA(0, 1), cA + hstep, voffA);
;         if (wr == 1) PG8_BAR;
;         PG8_WAIT_V(2); PG8_BAR;
;         PG8_STAGE(PG8_SB(1, 0), cB + kstep, voffB); PG8_STAGE(PG8_SA(1, 0), cA + kstep, voffA); PG8_STAGE(PG8_SB(1, 1), cB + hstep + kstep, voffB);
;         PG8_WAIT_V(6); PG8_BAR;
;     } else {
;         PG8_STAGE(PG8_SB(0, 0), cB, voffB); PG8_STAGE(PG8_SA(0, 0), cA, voffA); PG8_STAGE(PG8_SB(0, 1), cB + hstep, voffB); PG8_STAGE(PG8_SA(0, 1), cA + hstep, voffA);
;         if (wr == 1) PG8_BAR;
;         PG8_WAIT_V(4); PG8_BAR;
.LBB0_175:
	v_readlane_b32 s10, v252, 0
	v_readlane_b32 s11, v252, 1
	s_load_dword s46, s[10:11], 0x98
	s_andn2_b64 vcc, exec, s[4:5]
	s_cbranch_vccnz .LBB0_272
	v_lshrrev_b32_e32 v2, 1, v161
	v_lshrrev_b32_e32 v3, 5, v161
	v_and_b32_e32 v2, 24, v2
	v_and_b32_e32 v3, 4, v3
	v_bfe_u32 v4, v161, 2, 2
	v_lshlrev_b32_e32 v0, 4, v161
	v_and_b32_e32 v1, 32, v161
	v_bfe_u32 v10, v161, 2, 4
	v_or3_b32 v2, v3, v4, v2
	v_lshrrev_b32_e32 v3, 3, v161
	s_movk_i32 s4, 0x70
	v_bitop3_b32 v8, v0, v1, 48 bitop3:0x6c
	v_and_b32_e32 v9, 64, v161
	v_and_or_b32 v4, v3, s4, v10
	s_movk_i32 s4, 0x60
	v_add_u32_e32 v11, 0x2000, v0
	s_add_u32 s47, s92, 0x8200000
	v_or_b32_e32 v1, v8, v9
	v_and_or_b32 v3, v3, s4, v2
	v_lshrrev_b32_e32 v0, 7, v11
	s_movk_i32 s4, 0xf0
	s_addc_u32 s48, s93, 0
	s_lshr_b32 s3, s1, 6
	v_lshl_or_b32 v136, v3, 12, v1
	v_and_or_b32 v3, v0, s4, v10
	s_movk_i32 s4, 0xe0
	s_ashr_i32 s13, s12, 31
	s_ashr_i32 s7, s6, 31
	v_and_or_b32 v0, v0, s4, v2
	s_lshr_b32 s4, s1, 8
	s_lshl_b32 s49, s3, 10
	s_lshl_b64 s[10:11], s[12:13], 20
	s_lshl_b64 s[14:15], s[6:7], 20
	s_add_u32 s42, s47, s14
	s_addc_u32 s43, s48, s15
	s_add_u32 s40, s92, s10
	s_addc_u32 s41, s93, s11
	s_and_b32 s32, s6, -4
	s_cmp_eq_u32 s32, 8
	s_cselect_b32 s32, s42, s40
	s_cselect_b32 s10, s43, s41
	s_cselect_b32 s42, s40, s42
	s_cselect_b32 s43, s41, s43
	s_mov_b32 s40, s32
	s_mov_b32 s41, s10
	s_add_i32 s50, s49, 0
	s_add_i32 m0, s50, 0x10000
	v_lshl_or_b32 v140, v0, 12, v1
	global_load_lds_dwordx4 v136, s[42:43]
	s_add_i32 m0, s50, 0x12000
	s_add_u32 s14, s42, 0x80000
	global_load_lds_dwordx4 v140, s[42:43]
	s_addc_u32 s15, s43, 0
	s_add_i32 m0, s50, 0x14000
	v_lshl_or_b32 v134, v4, 12, v1
	global_load_lds_dwordx4 v136, s[14:15]
	s_add_i32 m0, s50, 0x16000


; #define PG8_STAGE(bufoff, gbase, voff) do { _Pragma("unroll") for (int _i = 0; _i < 2; ++_i) \
;         __builtin_amdgcn_global_load_lds((const unsigned*)((const char*)(gbase) + (voff)[_i]), (PG8_LAS unsigned*)(lds + (bufoff) + ldsw + _i * 8192), 16, 0, 0); } while (0)
; #define PG8_BAR __builtin_amdgcn_s_barrier()
; template <class Epi, class Sched, bool ALIGN_EPI = false, bool SP2 = false>
; __device__ __forceinline__ void gemm_phase(PG8_LAS unsigned char* lds, const Gemm g, const Sched& S, const Epi& E) {
;     ...
;         PG8_STAGE(PG8_SB(0, 0), cB, voffB); PG8_STAGE(PG8_SA(0, 0), cA, voffA); PG8_STAGE(PG8_SB(0, 1), cB + hstep, voffB); PG8_STAGE(PG8_SA(0, 1), cA + hstep, voffA);
;         if (wr == 1) PG8_BAR;
	s_add_i32 s51, s50, 0x2000
	global_load_lds_dwordx4 v140, s[14:15]
	s_mov_b32 m0, s50
	s_add_u32 s10, s40, 0x80000
	v_lshl_or_b32 v138, v3, 12, v1
	global_load_lds_dwordx4 v134, s[40:41]
	s_mov_b32 m0, s51
	s_addc_u32 s11, s41, 0
	s_add_i32 s52, s50, 0x4000
	global_load_lds_dwordx4 v138, s[40:41]
	s_mov_b32 m0, s52
	s_add_i32 s53, s50, 0x6000
	global_load_lds_dwordx4 v134, s[10:11]
	s_mov_b32 m0, s53
	v_mov_b32_e32 v143, 0
	global_load_lds_dwordx4 v138, s[10:11]
	v_mov_b32_e32 v137, v143
	v_mov_b32_e32 v141, v143
	v_mov_b32_e32 v135, v143
	v_mov_b32_e32 v139, v143
	s_cmp_eq_u32 s4, 1
	s_mov_b32 s11, 0
	v_lshl_add_u64 v[6:7], s[42:43], 0, v[136:137]
	v_lshl_add_u64 v[4:5], s[42:43], 0, v[140:141]
	v_lshl_add_u64 v[2:3], s[40:41], 0, v[134:135]
	v_lshl_add_u64 v[0:1], s[40:41], 0, v[138:139]
	s_cselect_b64 s[14:15], -1, 0
	s_cmp_lg_u32 s4, 1
	s_movk_i32 s54, 0x4000
	s_cbranch_scc1 .LBB0_178
	s_barrier

; template <class Epi, class Sched, bool ALIGN_EPI = false, bool SP2 = false>
; __device__ __forceinline__ void gemm_phase(PG8_LAS unsigned char* lds, const Gemm g, const Sched& S, const Epi& E) {
;     ...
;         const bool has_next = S.next(ui + 1, nxt);
;         const char* nA = has_next ? (const char*)g.A + (size_t)nxt.pm * tstep : cA; const char* nB = has_next ? (const char*)g.Bt + (size_t)nxt.pn * tstep : cB;
;     ...
; #pragma unroll
;         for (int a = 0; a < 2; ++a)
; #pragma unroll
;             for (int b = 0; b < 2; ++b)
; #pragma unroll
;                 for (int m = 0; m < 4; ++m)
; #pragma unroll
;                     for (int n = 0; n < 2; ++n) acc[a][b][m][n] = (f32x4){0.f, 0.f, 0.f, 0.f};
;         cur = nxt; cA = nA; cB = nB; ++ui;
.LBB0_187:
	s_and_b32 vcc_lo, s6, -8
	s_cmp_lg_u32 vcc_lo, 24
	s_cselect_b32 vcc_lo, 1, 0
	s_cmp_lg_u32 s6, 56
	s_cselect_b32 s32, vcc_lo, 0
	s_and_b32 vcc_lo, s0, 3
	s_lshl_b32 vcc_lo, vcc_lo, 12
	s_mul_i32 vcc_lo, vcc_lo, s32
	s_mulk_i32 s32, 0x3000
	s_sub_i32 s32, vcc_lo, s32
	v_add_u32_e32 v177, vcc_lo, v159
	v_add_u32_e32 v244, s32, v159
	v_add_u32_e32 v174, s82, v177
	v_add_u32_e32 v175, s83, v244
	s_ashr_i32 s35, s34, 31
	s_lshl_b64 s[36:37], s[34:35], 20
	s_add_u32 s36, s92, s36
	s_addc_u32 s37, s93, s37
	s_ashr_i32 s31, s30, 31
	s_lshl_b64 s[38:39], s[30:31], 20
	s_add_u32 s38, s47, s38
	s_addc_u32 s39, s48, s39
	s_and_b32 s1, s30, -4
	s_cmp_eq_u32 s1, 8
	s_cselect_b32 s1, s38, s36
	s_cselect_b32 s3, s39, s37
	s_cselect_b32 s38, s36, s38
	s_cselect_b32 s39, s37, s39
	s_mov_b32 s36, s1
	s_mov_b32 s37, s3
	s_and_b64 s[44:45], s[4:5], exec
	s_cselect_b32 s1, s37, s41
	s_cselect_b32 s3, s36, s40
	s_cselect_b32 s7, s39, s43
	s_cselect_b32 s10, s38, s42
	s_add_u32 s40, s40, 0x80080
	s_addc_u32 s41, s41, 0
	s_add_u32 s13, s42, 0x100
	s_waitcnt lgkmcnt(0)
	v_mov_b32_e32 v66, 0
	s_addc_u32 s31, s43, 0
	s_mov_b32 s33, -2
	v_mov_b32_e32 v67, v66
	v_mov_b32_e32 v68, v66
	v_mov_b32_e32 v69, v66
	v_mov_b32_e32 v74, v66
	v_mov_b32_e32 v75, v66
	v_mov_b32_e32 v76, v66
	v_mov_b32_e32 v77, v66
	v_mov_b32_e32 v70, v66
	v_mov_b32_e32 v71, v66
	v_mov_b32_e32 v72, v66
	v_mov_b32_e32 v73, v66
	v_mov_b32_e32 v78, v66
	v_mov_b32_e32 v79, v66
	v_mov_b32_e32 v80, v66
	v_mov_b32_e32 v81, v66
	v_mov_b32_e32 v82, v66
	v_mov_b32_e32 v83, v66
	v_mov_b32_e32 v84, v66
	v_mov_b32_e32 v85, v66
	v_mov_b32_e32 v86, v66
	v_mov_b32_e32 v87, v66
	v_mov_b32_e32 v88, v66
	v_mov_b32_e32 v89, v66
	v_mov_b32_e32 v90, v66
	v_mov_b32_e32 v91, v66
	v_mov_b32_e32 v92, v66
	v_mov_b32_e32 v93, v66
	v_mov_b32_e32 v94, v66
	v_mov_b32_e32 v95, v66
	v_mov_b32_e32 v96, v66
	v_mov_b32_e32 v97, v66
	v_mov_b32_e32 v0, v66
	v_mov_b32_e32 v1, v66
	v_mov_b32_e32 v2, v66
	v_mov_b32_e32 v3, v66
	v_mov_b32_e32 v4, v66
	v_mov_b32_e32 v5, v66
	v_mov_b32_e32 v6, v66
	v_mov_b32_e32 v7, v66
	v_mov_b32_e32 v8, v66
	v_mov_b32_e32 v9, v66
	v_mov_b32_e32 v10, v66
	v_mov_b32_e32 v11, v66
	v_mov_b32_e32 v12, v66
	v_mov_b32_e32 v13, v66
	v_mov_b32_e32 v14, v66
	v_mov_b32_e32 v15, v66
	v_mov_b32_e32 v16, v66
	v_mov_b32_e32 v17, v66
	v_mov_b32_e32 v18, v66
	v_mov_b32_e32 v19, v66
	v_mov_b32_e32 v20, v66
	v_mov_b32_e32 v21, v66
	v_mov_b32_e32 v22, v66
	v_mov_b32_e32 v23, v66
	v_mov_b32_e32 v24, v66
	v_mov_b32_e32 v25, v66
	v_mov_b32_e32 v26, v66
	v_mov_b32_e32 v27, v66
	v_mov_b32_e32 v28, v66
	v_mov_b32_e32 v29, v66
	v_mov_b32_e32 v30, v66
	v_mov_b32_e32 v31, v66
	v_mov_b32_e32 v98, v66
	v_mov_b32_e32 v99, v66
	v_mov_b32_e32 v100, v66
	v_mov_b32_e32 v101, v66
	v_mov_b32_e32 v102, v66
	v_mov_b32_e32 v103, v66
	v_mov_b32_e32 v104, v66
	v_mov_b32_e32 v105, v66
	v_mov_b32_e32 v106, v66
	v_mov_b32_e32 v107, v66
	v_mov_b32_e32 v108, v66
	v_mov_b32_e32 v109, v66
	v_mov_b32_e32 v110, v66
	v_mov_b32_e32 v111, v66
	v_mov_b32_e32 v112, v66
	v_mov_b32_e32 v113, v66
	v_mov_b32_e32 v114, v66
	v_mov_b32_e32 v115, v66
	v_mov_b32_e32 v116, v66
	v_mov_b32_e32 v117, v66
	v_mov_b32_e32 v118, v66
	v_mov_b32_e32 v119, v66
	v_mov_b32_e32 v120, v66
	v_mov_b32_e32 v121, v66
	v_mov_b32_e32 v122, v66
	v_mov_b32_e32 v123, v66
	v_mov_b32_e32 v124, v66
	v_mov_b32_e32 v125, v66
	v_mov_b32_e32 v126, v66
	v_mov_b32_e32 v127, v66
	v_mov_b32_e32 v128, v66
	v_mov_b32_e32 v129, v66
	v_mov_b32_e32 v32, v66
	v_mov_b32_e32 v33, v66
	v_mov_b32_e32 v34, v66
	v_mov_b32_e32 v35, v66
	v_mov_b32_e32 v36, v66
	v_mov_b32_e32 v37, v66
	v_mov_b32_e32 v38, v66
	v_mov_b32_e32 v39, v66
	v_mov_b32_e32 v40, v66
	v_mov_b32_e32 v41, v66
	v_mov_b32_e32 v42, v66
	v_mov_b32_e32 v43, v66
	v_mov_b32_e32 v44, v66
	v_mov_b32_e32 v45, v66
	v_mov_b32_e32 v46, v66
	v_mov_b32_e32 v47, v66
	v_mov_b32_e32 v48, v66
	v_mov_b32_e32 v49, v66
	v_mov_b32_e32 v50, v66
	v_mov_b32_e32 v51, v66
	v_mov_b32_e32 v52, v66
	v_mov_b32_e32 v53, v66
	v_mov_b32_e32 v54, v66
	v_mov_b32_e32 v55, v66
	v_mov_b32_e32 v56, v66
	v_mov_b32_e32 v57, v66
	v_mov_b32_e32 v58, v66
	v_mov_b32_e32 v59, v66
	v_mov_b32_e32 v60, v66
	v_mov_b32_e32 v61, v66
	v_mov_b32_e32 v62, v66
	v_mov_b32_e32 v63, v66

;     __device__ __forceinline__ void operator()(const f32x4 (&acc)[2][2][4][2], const pg8::Unit& u, int wr, int wc, int fr, int fq) const {
;     ...
;         const bool tr = (pn >= 8 && pn < 12) || (pn >= 24 && pn < 32);
;         unsigned char* base; int colt, ld;
;         if (pn < 24) { base = ws + WS_AQ + (size_t)(pn >> 2) * SZ1; colt = (pn & 3) * 256; ld = 1024; }
;         else { base = ws + WS_BVT + (size_t)((pn - 24) >> 3) * SZ2; colt = ((pn - 24) & 7) * 256; ld = 2048; }
;         if (tr) {
;             bf16_t* VO = (bf16_t*)base; const bool isb = pn >= 24;
;             bf16_t* T = (bf16_t*)(lds_epi + (wr * 4 + wc) * 2048);
;             const int lane = fq * 16 + fr, col = lane & 31, half = lane >> 5;
; #pragma unroll
;             for (int ai = 0; ai < 2; ++ai)
; #pragma unroll
;                 for (int m = 0; m < 4; ++m)
; #pragma unroll
;                     for (int bj = 0; bj < 2; ++bj) {
; #pragma unroll
;                         for (int n = 0; n < 2; ++n) { const f32x4 v = acc[ai][bj][m][n]; const unsigned w0 = pk2(v[0], v[1]), w1 = pk2(v[2], v[3]);
;                             bf16_t* p = T + (8 * fq + 4 * n) * 24 + fr;
;                             p[0] = (bf16_t)(w0 & 0xffffu); p[24] = (bf16_t)(w0 >> 16); p[48] = (bf16_t)(w1 & 0xffffu); p[72] = (bf16_t)(w1 >> 16); }
;                         asm volatile("s_waitcnt lgkmcnt(0)" ::: "memory");
;                         const u32x4 w = *(const u32x4*)(T + col * 24 + half * 8);
;                         asm volatile("s_waitcnt lgkmcnt(0)" ::: "memory");
;                         const int dvg = colt + bj * 128 + wc * 32 + col;
;                         if (isb) { const size_t gc = (size_t)u.pm * 4 + ai * 2 + wr;
;                             *(u32x4*)(VO + ((((gc * 4 + (dvg >> 9)) * 16 + ((dvg >> 5) & 15)) * 4 + m) * 64 + half * 32 + col) * 8) = w; }
;                         else *(u32x4*)(VO + (size_t)dvg * MR + (size_t)(u.pm * 256 + ai * 128 + wr * 64 + m * 16 + half * 8)) = w;
;                     }
;         } else {
;             bf16_t* O = (bf16_t*)base; const int col0 = colt + wc * 32 + 8 * fq;
; #pragma unroll
;             for (int ai = 0; ai < 2; ++ai)
; #pragma unroll
;                 for (int m = 0; m < 4; ++m) { bf16_t* rowp = O + (size_t)(row0 + ai * 128 + m * 16) * ld + col0;
; #pragma unroll
.LBB0_197:
	s_and_b32 s7, s6, -8
	s_cmp_lg_u32 s7, 24
	s_cselect_b64 s[56:57], -1, 0
	s_lshl_b32 s7, s6, 8
	s_and_b32 s10, s3, s7
	s_and_b32 s3, s6, -4
	s_cmp_eq_u32 s3, 8
	s_cselect_b32 s3, s10, s1
	s_cselect_b32 s10, s1, s10
	s_cselect_b32 s42, 0x8200, s42
	v_add_u32_e32 v156, s3, v158
	s_mov_b64 s[44:45], -1
	s_and_b64 vcc, exec, s[56:57]
	v_cvt_pk_bf16_f32 v130, v60, v61
	v_cvt_pk_bf16_f32 v131, v62, v63
	v_cvt_pk_bf16_f32 v132, v56, v57
	v_cvt_pk_bf16_f32 v133, v58, v59
	v_cvt_pk_bf16_f32 v126, v126, v127
	v_cvt_pk_bf16_f32 v127, v128, v129
	v_cvt_pk_bf16_f32 v128, v122, v123
	v_cvt_pk_bf16_f32 v129, v124, v125
	v_cvt_pk_bf16_f32 v122, v52, v53
	v_cvt_pk_bf16_f32 v123, v54, v55
	v_cvt_pk_bf16_f32 v124, v48, v49
	v_cvt_pk_bf16_f32 v125, v50, v51
	v_cvt_pk_bf16_f32 v118, v118, v119
	v_cvt_pk_bf16_f32 v119, v120, v121
	v_cvt_pk_bf16_f32 v120, v114, v115
	v_cvt_pk_bf16_f32 v121, v116, v117
	v_cvt_pk_bf16_f32 v114, v44, v45
	v_cvt_pk_bf16_f32 v115, v46, v47
	v_cvt_pk_bf16_f32 v116, v40, v41
	v_cvt_pk_bf16_f32 v117, v42, v43
	v_cvt_pk_bf16_f32 v110, v110, v111
	v_cvt_pk_bf16_f32 v111, v112, v113
	v_cvt_pk_bf16_f32 v112, v106, v107
	v_cvt_pk_bf16_f32 v113, v108, v109
	v_cvt_pk_bf16_f32 v106, v36, v37
	v_cvt_pk_bf16_f32 v107, v38, v39
	v_cvt_pk_bf16_f32 v108, v32, v33
	v_cvt_pk_bf16_f32 v109, v34, v35
	v_cvt_pk_bf16_f32 v102, v102, v103
	v_cvt_pk_bf16_f32 v103, v104, v105
	v_cvt_pk_bf16_f32 v104, v98, v99
	v_cvt_pk_bf16_f32 v105, v100, v101
	v_cvt_pk_bf16_f32 v98, v28, v29
	v_cvt_pk_bf16_f32 v99, v30, v31
	v_cvt_pk_bf16_f32 v100, v24, v25
	v_cvt_pk_bf16_f32 v101, v26, v27
	v_cvt_pk_bf16_f32 v94, v94, v95
	v_cvt_pk_bf16_f32 v95, v96, v97
	v_cvt_pk_bf16_f32 v96, v90, v91
	v_cvt_pk_bf16_f32 v97, v92, v93
	v_cvt_pk_bf16_f32 v90, v20, v21
	v_cvt_pk_bf16_f32 v91, v22, v23
	v_cvt_pk_bf16_f32 v92, v16, v17
	v_cvt_pk_bf16_f32 v93, v18, v19
	v_cvt_pk_bf16_f32 v86, v86, v87
	v_cvt_pk_bf16_f32 v87, v88, v89
	v_cvt_pk_bf16_f32 v88, v82, v83
	v_cvt_pk_bf16_f32 v89, v84, v85
	v_cvt_pk_bf16_f32 v82, v12, v13
	v_cvt_pk_bf16_f32 v83, v14, v15
	v_cvt_pk_bf16_f32 v84, v8, v9
	v_cvt_pk_bf16_f32 v85, v10, v11
	v_cvt_pk_bf16_f32 v78, v78, v79
	v_cvt_pk_bf16_f32 v79, v80, v81
	v_cvt_pk_bf16_f32 v80, v70, v71
	v_cvt_pk_bf16_f32 v81, v72, v73
	v_cvt_pk_bf16_f32 v70, v4, v5
	v_cvt_pk_bf16_f32 v71, v6, v7
	v_cvt_pk_bf16_f32 v72, v0, v1
	v_cvt_pk_bf16_f32 v73, v2, v3
	v_cvt_pk_bf16_f32 v64, v74, v75
	v_cvt_pk_bf16_f32 v65, v76, v77
	v_cvt_pk_bf16_f32 v66, v66, v67
	v_cvt_pk_bf16_f32 v67, v68, v69
	s_cbranch_vccz .LBB0_199
	s_and_b32 s32, s0, 3
	s_lshl_b32 s32, s32, 5
	v_add_u32_e32 v68, s32, v162
	v_or_b32_e32 v68, s10, v68
	v_lshlrev_b32_e32 v142, 1, v68
	v_lshl_add_u64 v[68:69], s[40:41], 0, v[142:143]
	v_mad_i64_i32 v[74:75], s[44:45], s42, v156, 0
	v_lshl_add_u64 v[74:75], v[74:75], 1, v[68:69]
	global_store_dwordx4 v[74:75], v[130:133], off nt
	global_store_dwordx4 v[74:75], v[126:129], off offset:64 nt
	v_or_b32_e32 v74, 16, v156
	v_mad_i64_i32 v[74:75], s[44:45], s42, v74, 0
	v_lshl_add_u64 v[74:75], v[74:75], 1, v[68:69]
	global_store_dwordx4 v[74:75], v[122:125], off nt
	global_store_dwordx4 v[74:75], v[118:121], off offset:64 nt
	v_or_b32_e32 v74, 32, v156
	v_mad_i64_i32 v[74:75], s[44:45], s42, v74, 0
	v_lshl_add_u64 v[74:75], v[74:75], 1, v[68:69]
	global_store_dwordx4 v[74:75], v[114:117], off nt
	global_store_dwordx4 v[74:75], v[110:113], off offset:64 nt
	v_or_b32_e32 v74, 48, v156
	v_mad_i64_i32 v[74:75], s[44:45], s42, v74, 0
	v_lshl_add_u64 v[74:75], v[74:75], 1, v[68:69]
	global_store_dwordx4 v[74:75], v[106:109], off nt
	global_store_dwordx4 v[74:75], v[102:105], off offset:64 nt
	v_add_u32_e32 v74, 0x80, v156
	v_mad_i64_i32 v[74:75], s[44:45], s42, v74, 0
	v_lshl_add_u64 v[74:75], v[74:75], 1, v[68:69]
	global_store_dwordx4 v[74:75], v[98:101], off nt
	global_store_dwordx4 v[74:75], v[94:97], off offset:64 nt
	v_add_u32_e32 v74, 0x90, v156
	v_mad_i64_i32 v[74:75], s[44:45], s42, v74, 0
	v_lshl_add_u64 v[74:75], v[74:75], 1, v[68:69]
	global_store_dwordx4 v[74:75], v[90:93], off nt
	global_store_dwordx4 v[74:75], v[86:89], off offset:64 nt
	v_add_u32_e32 v74, 0xa0, v156
	v_mad_i64_i32 v[74:75], s[44:45], s42, v74, 0
	v_lshl_add_u64 v[74:75], v[74:75], 1, v[68:69]
	global_store_dwordx4 v[74:75], v[82:85], off nt
	global_store_dwordx4 v[74:75], v[78:81], off offset:64 nt
	v_add_u32_e32 v74, 0xb0, v156
	v_mad_i64_i32 v[74:75], s[42:43], s42, v74, 0
	v_lshl_add_u64 v[68:69], v[74:75], 1, v[68:69]
	global_store_dwordx4 v[68:69], v[70:73], off nt
	global_store_dwordx4 v[68:69], v[64:67], off offset:64 nt
	s_mov_b64 s[44:45], 0
